# P3 queue order: conv items start after 704 heavy attention units (was 768), copies last, on q2
# speedup vs baseline: 1.0057x; 1.0057x over previous
; template<int THRL,class Extra> __device__ __forceinline__ void attn_phase_dyn(char*lds,const AttnTensors&T,unsigned*ctr,const Extra&X,int nextra){
;     ...
;   for(;;){
;     if(tid==0){uw[0]=nxt;}
;     asm volatile("s_waitcnt lgkmcnt(0)\n\ts_barrier":::"memory");
;     const unsigned u=(unsigned)__builtin_amdgcn_readfirstlane((int)uw[0]);
;     if(u>=(unsigned)(BATCH*NHEAD*NQB+nextra))break;
;     if(u>=(unsigned)(BATCH*NHEAD*NQB)){ if(tid==0)nxt=G_+__hip_atomic_fetch_add(ctr,1u,__ATOMIC_RELAXED,__HIP_MEMORY_SCOPE_AGENT);
;       X((int)u-BATCH*NHEAD*NQB); asm volatile("s_waitcnt lgkmcnt(0)\n\ts_barrier":::"memory"); continue; }
;     const int qb=NQB-1-(int)(u/(BATCH*NHEAD)), bh=(int)(u%(BATCH*NHEAD));
.LBB0_343:
	s_and_saveexec_b64 s[6:7], s[18:19]
	ds_write_b32 v201, v213 offset:49152
	s_or_b64 exec, exec, s[6:7]
	s_waitcnt lgkmcnt(0)
	s_barrier
	ds_read_b32 v1, v201 offset:49152
	s_mov_b64 s[6:7], -1
	s_waitcnt lgkmcnt(0)
	v_readfirstlane_b32 s63, v1
	s_cmpk_lt_u32 s63, 0x2c0
	s_cbranch_scc1 .Lqmap_done
	s_cmpk_gt_u32 s63, 0x4ff
	s_cbranch_scc1 .Lqmap_done
	s_add_i32 s80, s63, 0x140
	s_cmpk_lt_u32 s63, 0x3c0
	s_cbranch_scc1 .Lqmap_set
	s_add_i32 s80, s63, 0xffffff00
